# final phase: each workgroup takes the 64 rows whose y tiles its own XCD produced in GEMM3 (8 consecutive rows per wave)
# baseline (speedup 1.0000x reference)
.LBB0_942:
	s_or_b64 exec, exec, s[2:3]
	s_waitcnt lgkmcnt(0)
	v_add_u32_e32 v0, s64, v196
	s_movk_i32 s0, 0x4000
	v_cmp_gt_i32_e32 vcc, s0, v0
	s_barrier
	v_readfirstlane_b32 s0, v196
	v_readlane_b32 s8, v236, 3
	v_readlane_b32 s9, v236, 4
	v_lshlrev_b32_e32 v136, 4, v197
	v_lshlrev_b32_e32 v137, 3, v197
	v_lshlrev_b32_e32 v138, 2, v197
	v_xor_b32_e32 v130, 32, v197
	v_lshlrev_b32_e32 v130, 2, v130
	v_xor_b32_e32 v131, 16, v197
	v_lshlrev_b32_e32 v131, 2, v131
	v_xor_b32_e32 v132, 8, v197
	v_lshlrev_b32_e32 v132, 2, v132
	v_xor_b32_e32 v133, 4, v197
	v_lshlrev_b32_e32 v133, 2, v133
	v_xor_b32_e32 v134, 2, v197
	v_lshlrev_b32_e32 v134, 2, v134
	v_xor_b32_e32 v135, 1, v197
	v_lshlrev_b32_e32 v135, 2, v135
	v_mov_b32_e32 v154, 0x358637bd
	s_lshr_b32 s1, s64, 3
	s_and_b32 s2, s1, 7
	s_lshl_b32 s2, s2, 11
	s_lshr_b32 s1, s1, 3
	s_lshl_b32 s1, s1, 6
	s_add_u32 s24, s2, s1
	s_lshl_b32 s0, s0, 3
	s_add_u32 s24, s24, s0
	s_mov_b32 s25, s24
	s_add_u32 s2, s60, 0x1000
	s_addc_u32 s3, s61, 0
	global_load_dwordx4 v[96:99], v136, s[60:61] offset:0
	global_load_dwordx4 v[100:103], v136, s[60:61] offset:1024
	global_load_dwordx4 v[104:107], v136, s[60:61] offset:2048
	global_load_dwordx4 v[108:111], v136, s[60:61] offset:3072
	global_load_dwordx4 v[112:115], v136, s[2:3] offset:0
	global_load_dwordx4 v[116:119], v136, s[2:3] offset:1024
	global_load_dwordx4 v[120:123], v136, s[2:3] offset:2048
	global_load_dwordx4 v[124:127], v136, s[2:3] offset:3072
	s_lshl_b32 s1, s24, 13
	s_add_u32 s10, s8, s1
	s_addc_u32 s11, s9, 0
	s_add_u32 s12, s10, 0x1000
	s_addc_u32 s13, s11, 0
	s_lshl_b32 s1, s24, 12
	s_add_u32 s18, s54, s1
	s_addc_u32 s19, s55, 0
	s_lshl_b32 s1, s24, 7
	s_add_u32 s20, s74, s1
	s_addc_u32 s21, s75, 0
	v_mov_b32_e32 v128, 0
	s_mov_b32 exec_hi, 0
	global_load_dword v128, v138, s[20:21]
	s_mov_b64 exec, -1
	global_load_dwordx2 v[64:65], v137, s[18:19] offset:0 nt
	global_load_dwordx2 v[66:67], v137, s[18:19] offset:512 nt
	global_load_dwordx2 v[68:69], v137, s[18:19] offset:1024 nt
	global_load_dwordx2 v[70:71], v137, s[18:19] offset:1536 nt
	global_load_dwordx2 v[72:73], v137, s[18:19] offset:2048 nt
	global_load_dwordx2 v[74:75], v137, s[18:19] offset:2560 nt
	global_load_dwordx2 v[76:77], v137, s[18:19] offset:3072 nt
	global_load_dwordx2 v[78:79], v137, s[18:19] offset:3584 nt
	global_load_dwordx4 v[0:3], v136, s[10:11] offset:0 nt
	global_load_dwordx4 v[4:7], v136, s[10:11] offset:1024 nt
	global_load_dwordx4 v[8:11], v136, s[10:11] offset:2048 nt
	global_load_dwordx4 v[12:15], v136, s[10:11] offset:3072 nt
	global_load_dwordx4 v[16:19], v136, s[12:13] offset:0 nt
	global_load_dwordx4 v[20:23], v136, s[12:13] offset:1024 nt
	global_load_dwordx4 v[24:27], v136, s[12:13] offset:2048 nt
	global_load_dwordx4 v[28:31], v136, s[12:13] offset:3072 nt
	s_add_u32 s24, s24, 1
	s_mov_b32 s26, 0
.Lfin_loop:
	s_lshl_b32 s1, s24, 13
	s_add_u32 s10, s8, s1
	s_addc_u32 s11, s9, 0
	s_add_u32 s12, s10, 0x1000
	s_addc_u32 s13, s11, 0
	s_lshl_b32 s1, s24, 12
	s_add_u32 s18, s54, s1
	s_addc_u32 s19, s55, 0
	s_lshl_b32 s1, s24, 7
	s_add_u32 s20, s74, s1
	s_addc_u32 s21, s75, 0
	v_mov_b32_e32 v129, 0
	s_mov_b32 exec_hi, 0
	global_load_dword v129, v138, s[20:21]
	s_mov_b64 exec, -1
	global_load_dwordx2 v[80:81], v137, s[18:19] offset:0 nt
	global_load_dwordx2 v[82:83], v137, s[18:19] offset:512 nt
	global_load_dwordx2 v[84:85], v137, s[18:19] offset:1024 nt
	global_load_dwordx2 v[86:87], v137, s[18:19] offset:1536 nt
	global_load_dwordx2 v[88:89], v137, s[18:19] offset:2048 nt
	global_load_dwordx2 v[90:91], v137, s[18:19] offset:2560 nt
	global_load_dwordx2 v[92:93], v137, s[18:19] offset:3072 nt
	global_load_dwordx2 v[94:95], v137, s[18:19] offset:3584 nt
	global_load_dwordx4 v[32:35], v136, s[10:11] offset:0 nt
	global_load_dwordx4 v[36:39], v136, s[10:11] offset:1024 nt
	global_load_dwordx4 v[40:43], v136, s[10:11] offset:2048 nt
	global_load_dwordx4 v[44:47], v136, s[10:11] offset:3072 nt
	global_load_dwordx4 v[48:51], v136, s[12:13] offset:0 nt
	global_load_dwordx4 v[52:55], v136, s[12:13] offset:1024 nt
	global_load_dwordx4 v[56:59], v136, s[12:13] offset:2048 nt
	global_load_dwordx4 v[60:63], v136, s[12:13] offset:3072 nt
	s_add_u32 s24, s24, 1
	s_waitcnt vmcnt(17)
	v_mov_b32_e32 v140, v128
	ds_bpermute_b32 v141, v130, v140
	s_waitcnt lgkmcnt(0)
	v_add_f32_e32 v140, v140, v141
	ds_bpermute_b32 v141, v131, v140
	s_waitcnt lgkmcnt(0)
	v_add_f32_e32 v140, v140, v141
	ds_bpermute_b32 v141, v132, v140
	s_waitcnt lgkmcnt(0)
	v_add_f32_e32 v140, v140, v141
	ds_bpermute_b32 v141, v133, v140
	s_waitcnt lgkmcnt(0)
	v_add_f32_e32 v140, v140, v141
	ds_bpermute_b32 v141, v134, v140
	s_waitcnt lgkmcnt(0)
	v_add_f32_e32 v140, v140, v141
	ds_bpermute_b32 v141, v135, v140
	s_waitcnt lgkmcnt(0)
	v_add_f32_e32 v140, v140, v141
	v_fmamk_f32 v140, v140, 0x3a000000, v154
	s_mov_b32 s1, 0x800000
	v_mul_f32_e32 v142, 0x4b800000, v140
	v_cmp_gt_f32_e64 s[2:3], s1, v140
	s_nop 1
	v_cndmask_b32_e64 v140, v140, v142, s[2:3]
	v_rsq_f32_e32 v140, v140
	s_nop 0
	v_mul_f32_e32 v142, 0x45800000, v140
	v_cndmask_b32_e64 v144, v140, v142, s[2:3]
	s_lshl_b32 s1, s25, 13
	s_add_u32 s14, s62, s1
	s_addc_u32 s15, s63, 0
	s_add_u32 s16, s14, 0x1000
	s_addc_u32 s17, s15, 0
	s_add_u32 s25, s25, 1
	v_lshlrev_b32_e32 v146, 16, v64
	v_and_b32_e32 v147, 0xffff0000, v64
	v_lshlrev_b32_e32 v148, 16, v65
	v_and_b32_e32 v149, 0xffff0000, v65
	v_pk_mul_f32 v[146:147], v[144:145], v[146:147] op_sel_hi:[0,1]
	v_pk_mul_f32 v[148:149], v[144:145], v[148:149] op_sel_hi:[0,1]
	v_pk_fma_f32 v[150:151], v[96:97], v[146:147], v[0:1]
	v_pk_fma_f32 v[152:153], v[98:99], v[148:149], v[2:3]
	global_store_dwordx4 v136, v[150:153], s[14:15] offset:0 nt
	v_lshlrev_b32_e32 v146, 16, v66
	v_and_b32_e32 v147, 0xffff0000, v66
	v_lshlrev_b32_e32 v148, 16, v67
	v_and_b32_e32 v149, 0xffff0000, v67
	v_pk_mul_f32 v[146:147], v[144:145], v[146:147] op_sel_hi:[0,1]
	v_pk_mul_f32 v[148:149], v[144:145], v[148:149] op_sel_hi:[0,1]
	v_pk_fma_f32 v[150:151], v[100:101], v[146:147], v[4:5]
	v_pk_fma_f32 v[152:153], v[102:103], v[148:149], v[6:7]
	global_store_dwordx4 v136, v[150:153], s[14:15] offset:1024 nt
	v_lshlrev_b32_e32 v146, 16, v68
	v_and_b32_e32 v147, 0xffff0000, v68
	v_lshlrev_b32_e32 v148, 16, v69
	v_and_b32_e32 v149, 0xffff0000, v69
	v_pk_mul_f32 v[146:147], v[144:145], v[146:147] op_sel_hi:[0,1]
	v_pk_mul_f32 v[148:149], v[144:145], v[148:149] op_sel_hi:[0,1]
	v_pk_fma_f32 v[150:151], v[104:105], v[146:147], v[8:9]
	v_pk_fma_f32 v[152:153], v[106:107], v[148:149], v[10:11]
	global_store_dwordx4 v136, v[150:153], s[14:15] offset:2048 nt
	v_lshlrev_b32_e32 v146, 16, v70
	v_and_b32_e32 v147, 0xffff0000, v70
	v_lshlrev_b32_e32 v148, 16, v71
	v_and_b32_e32 v149, 0xffff0000, v71
	v_pk_mul_f32 v[146:147], v[144:145], v[146:147] op_sel_hi:[0,1]
	v_pk_mul_f32 v[148:149], v[144:145], v[148:149] op_sel_hi:[0,1]
	v_pk_fma_f32 v[150:151], v[108:109], v[146:147], v[12:13]
	v_pk_fma_f32 v[152:153], v[110:111], v[148:149], v[14:15]
	global_store_dwordx4 v136, v[150:153], s[14:15] offset:3072 nt
	v_lshlrev_b32_e32 v146, 16, v72
	v_and_b32_e32 v147, 0xffff0000, v72
	v_lshlrev_b32_e32 v148, 16, v73
	v_and_b32_e32 v149, 0xffff0000, v73
	v_pk_mul_f32 v[146:147], v[144:145], v[146:147] op_sel_hi:[0,1]
	v_pk_mul_f32 v[148:149], v[144:145], v[148:149] op_sel_hi:[0,1]
	v_pk_fma_f32 v[150:151], v[112:113], v[146:147], v[16:17]
	v_pk_fma_f32 v[152:153], v[114:115], v[148:149], v[18:19]
	global_store_dwordx4 v136, v[150:153], s[16:17] offset:0 nt
	v_lshlrev_b32_e32 v146, 16, v74
	v_and_b32_e32 v147, 0xffff0000, v74
	v_lshlrev_b32_e32 v148, 16, v75
	v_and_b32_e32 v149, 0xffff0000, v75
	v_pk_mul_f32 v[146:147], v[144:145], v[146:147] op_sel_hi:[0,1]
	v_pk_mul_f32 v[148:149], v[144:145], v[148:149] op_sel_hi:[0,1]
	v_pk_fma_f32 v[150:151], v[116:117], v[146:147], v[20:21]
	v_pk_fma_f32 v[152:153], v[118:119], v[148:149], v[22:23]
	global_store_dwordx4 v136, v[150:153], s[16:17] offset:1024 nt
	v_lshlrev_b32_e32 v146, 16, v76
	v_and_b32_e32 v147, 0xffff0000, v76
	v_lshlrev_b32_e32 v148, 16, v77
	v_and_b32_e32 v149, 0xffff0000, v77
	v_pk_mul_f32 v[146:147], v[144:145], v[146:147] op_sel_hi:[0,1]
	v_pk_mul_f32 v[148:149], v[144:145], v[148:149] op_sel_hi:[0,1]
	v_pk_fma_f32 v[150:151], v[120:121], v[146:147], v[24:25]
	v_pk_fma_f32 v[152:153], v[122:123], v[148:149], v[26:27]
	global_store_dwordx4 v136, v[150:153], s[16:17] offset:2048 nt
	v_lshlrev_b32_e32 v146, 16, v78
	v_and_b32_e32 v147, 0xffff0000, v78
	v_lshlrev_b32_e32 v148, 16, v79
	v_and_b32_e32 v149, 0xffff0000, v79
	v_pk_mul_f32 v[146:147], v[144:145], v[146:147] op_sel_hi:[0,1]
	v_pk_mul_f32 v[148:149], v[144:145], v[148:149] op_sel_hi:[0,1]
	v_pk_fma_f32 v[150:151], v[124:125], v[146:147], v[28:29]
	v_pk_fma_f32 v[152:153], v[126:127], v[148:149], v[30:31]
	global_store_dwordx4 v136, v[150:153], s[16:17] offset:3072 nt
	s_cmp_eq_u32 s26, 3
	s_cbranch_scc1 .Lfin_last
	s_lshl_b32 s1, s24, 13
	s_add_u32 s10, s8, s1
	s_addc_u32 s11, s9, 0
	s_add_u32 s12, s10, 0x1000
	s_addc_u32 s13, s11, 0
	s_lshl_b32 s1, s24, 12
	s_add_u32 s18, s54, s1
	s_addc_u32 s19, s55, 0
	s_lshl_b32 s1, s24, 7
	s_add_u32 s20, s74, s1
	s_addc_u32 s21, s75, 0
	v_mov_b32_e32 v128, 0
	s_mov_b32 exec_hi, 0
	global_load_dword v128, v138, s[20:21]
	s_mov_b64 exec, -1
	global_load_dwordx2 v[64:65], v137, s[18:19] offset:0 nt
	global_load_dwordx2 v[66:67], v137, s[18:19] offset:512 nt
	global_load_dwordx2 v[68:69], v137, s[18:19] offset:1024 nt
	global_load_dwordx2 v[70:71], v137, s[18:19] offset:1536 nt
	global_load_dwordx2 v[72:73], v137, s[18:19] offset:2048 nt
	global_load_dwordx2 v[74:75], v137, s[18:19] offset:2560 nt
	global_load_dwordx2 v[76:77], v137, s[18:19] offset:3072 nt
	global_load_dwordx2 v[78:79], v137, s[18:19] offset:3584 nt
	global_load_dwordx4 v[0:3], v136, s[10:11] offset:0 nt
	global_load_dwordx4 v[4:7], v136, s[10:11] offset:1024 nt
	global_load_dwordx4 v[8:11], v136, s[10:11] offset:2048 nt
	global_load_dwordx4 v[12:15], v136, s[10:11] offset:3072 nt
	global_load_dwordx4 v[16:19], v136, s[12:13] offset:0 nt
	global_load_dwordx4 v[20:23], v136, s[12:13] offset:1024 nt
	global_load_dwordx4 v[24:27], v136, s[12:13] offset:2048 nt
	global_load_dwordx4 v[28:31], v136, s[12:13] offset:3072 nt
	s_add_u32 s24, s24, 1
	s_waitcnt vmcnt(17)
	s_branch .Lfin_odd

.Lfin_odd:
	v_mov_b32_e32 v140, v129
	ds_bpermute_b32 v141, v130, v140
	s_waitcnt lgkmcnt(0)
	v_add_f32_e32 v140, v140, v141
	ds_bpermute_b32 v141, v131, v140
	s_waitcnt lgkmcnt(0)
	v_add_f32_e32 v140, v140, v141
	ds_bpermute_b32 v141, v132, v140
	s_waitcnt lgkmcnt(0)
	v_add_f32_e32 v140, v140, v141
	ds_bpermute_b32 v141, v133, v140
	s_waitcnt lgkmcnt(0)
	v_add_f32_e32 v140, v140, v141
	ds_bpermute_b32 v141, v134, v140
	s_waitcnt lgkmcnt(0)
	v_add_f32_e32 v140, v140, v141
	ds_bpermute_b32 v141, v135, v140
	s_waitcnt lgkmcnt(0)
	v_add_f32_e32 v140, v140, v141
	v_fmamk_f32 v140, v140, 0x3a000000, v154
	s_mov_b32 s1, 0x800000
	v_mul_f32_e32 v142, 0x4b800000, v140
	v_cmp_gt_f32_e64 s[2:3], s1, v140
	s_nop 1
	v_cndmask_b32_e64 v140, v140, v142, s[2:3]
	v_rsq_f32_e32 v140, v140
	s_nop 0
	v_mul_f32_e32 v142, 0x45800000, v140
	v_cndmask_b32_e64 v144, v140, v142, s[2:3]
	s_lshl_b32 s1, s25, 13
	s_add_u32 s14, s62, s1
	s_addc_u32 s15, s63, 0
	s_add_u32 s16, s14, 0x1000
	s_addc_u32 s17, s15, 0
	s_add_u32 s25, s25, 1
	v_lshlrev_b32_e32 v146, 16, v80
	v_and_b32_e32 v147, 0xffff0000, v80
	v_lshlrev_b32_e32 v148, 16, v81
	v_and_b32_e32 v149, 0xffff0000, v81
	v_pk_mul_f32 v[146:147], v[144:145], v[146:147] op_sel_hi:[0,1]
	v_pk_mul_f32 v[148:149], v[144:145], v[148:149] op_sel_hi:[0,1]
	v_pk_fma_f32 v[150:151], v[96:97], v[146:147], v[32:33]
	v_pk_fma_f32 v[152:153], v[98:99], v[148:149], v[34:35]
	global_store_dwordx4 v136, v[150:153], s[14:15] offset:0 nt
	v_lshlrev_b32_e32 v146, 16, v82
	v_and_b32_e32 v147, 0xffff0000, v82
	v_lshlrev_b32_e32 v148, 16, v83
	v_and_b32_e32 v149, 0xffff0000, v83
	v_pk_mul_f32 v[146:147], v[144:145], v[146:147] op_sel_hi:[0,1]
	v_pk_mul_f32 v[148:149], v[144:145], v[148:149] op_sel_hi:[0,1]
	v_pk_fma_f32 v[150:151], v[100:101], v[146:147], v[36:37]
	v_pk_fma_f32 v[152:153], v[102:103], v[148:149], v[38:39]
	global_store_dwordx4 v136, v[150:153], s[14:15] offset:1024 nt
	v_lshlrev_b32_e32 v146, 16, v84
	v_and_b32_e32 v147, 0xffff0000, v84
	v_lshlrev_b32_e32 v148, 16, v85
	v_and_b32_e32 v149, 0xffff0000, v85
	v_pk_mul_f32 v[146:147], v[144:145], v[146:147] op_sel_hi:[0,1]
	v_pk_mul_f32 v[148:149], v[144:145], v[148:149] op_sel_hi:[0,1]
	v_pk_fma_f32 v[150:151], v[104:105], v[146:147], v[40:41]
	v_pk_fma_f32 v[152:153], v[106:107], v[148:149], v[42:43]
	global_store_dwordx4 v136, v[150:153], s[14:15] offset:2048 nt
	v_lshlrev_b32_e32 v146, 16, v86
	v_and_b32_e32 v147, 0xffff0000, v86
	v_lshlrev_b32_e32 v148, 16, v87
	v_and_b32_e32 v149, 0xffff0000, v87
	v_pk_mul_f32 v[146:147], v[144:145], v[146:147] op_sel_hi:[0,1]
	v_pk_mul_f32 v[148:149], v[144:145], v[148:149] op_sel_hi:[0,1]
	v_pk_fma_f32 v[150:151], v[108:109], v[146:147], v[44:45]
	v_pk_fma_f32 v[152:153], v[110:111], v[148:149], v[46:47]
	global_store_dwordx4 v136, v[150:153], s[14:15] offset:3072 nt
	v_lshlrev_b32_e32 v146, 16, v88
	v_and_b32_e32 v147, 0xffff0000, v88
	v_lshlrev_b32_e32 v148, 16, v89
	v_and_b32_e32 v149, 0xffff0000, v89
	v_pk_mul_f32 v[146:147], v[144:145], v[146:147] op_sel_hi:[0,1]
	v_pk_mul_f32 v[148:149], v[144:145], v[148:149] op_sel_hi:[0,1]
	v_pk_fma_f32 v[150:151], v[112:113], v[146:147], v[48:49]
	v_pk_fma_f32 v[152:153], v[114:115], v[148:149], v[50:51]
	global_store_dwordx4 v136, v[150:153], s[16:17] offset:0 nt
	v_lshlrev_b32_e32 v146, 16, v90
	v_and_b32_e32 v147, 0xffff0000, v90
	v_lshlrev_b32_e32 v148, 16, v91
	v_and_b32_e32 v149, 0xffff0000, v91
	v_pk_mul_f32 v[146:147], v[144:145], v[146:147] op_sel_hi:[0,1]
	v_pk_mul_f32 v[148:149], v[144:145], v[148:149] op_sel_hi:[0,1]
	v_pk_fma_f32 v[150:151], v[116:117], v[146:147], v[52:53]
	v_pk_fma_f32 v[152:153], v[118:119], v[148:149], v[54:55]
	global_store_dwordx4 v136, v[150:153], s[16:17] offset:1024 nt
	v_lshlrev_b32_e32 v146, 16, v92
	v_and_b32_e32 v147, 0xffff0000, v92
	v_lshlrev_b32_e32 v148, 16, v93
	v_and_b32_e32 v149, 0xffff0000, v93
	v_pk_mul_f32 v[146:147], v[144:145], v[146:147] op_sel_hi:[0,1]
	v_pk_mul_f32 v[148:149], v[144:145], v[148:149] op_sel_hi:[0,1]
	v_pk_fma_f32 v[150:151], v[120:121], v[146:147], v[56:57]
	v_pk_fma_f32 v[152:153], v[122:123], v[148:149], v[58:59]
	global_store_dwordx4 v136, v[150:153], s[16:17] offset:2048 nt
	v_lshlrev_b32_e32 v146, 16, v94
	v_and_b32_e32 v147, 0xffff0000, v94
	v_lshlrev_b32_e32 v148, 16, v95
	v_and_b32_e32 v149, 0xffff0000, v95
	v_pk_mul_f32 v[146:147], v[144:145], v[146:147] op_sel_hi:[0,1]
	v_pk_mul_f32 v[148:149], v[144:145], v[148:149] op_sel_hi:[0,1]
	v_pk_fma_f32 v[150:151], v[124:125], v[146:147], v[60:61]
	v_pk_fma_f32 v[152:153], v[126:127], v[148:149], v[62:63]
	global_store_dwordx4 v136, v[150:153], s[16:17] offset:3072 nt
	s_add_u32 s26, s26, 1
	s_cmp_lt_u32 s26, 4
	s_cbranch_scc1 .Lfin_loop
